# L1 attention: K-fragment ds_reads batched with counted waits, V^T reads hoisted above softmax
# speedup vs baseline: 1.0145x; 1.0081x over previous
.LBB0_807:
	v_exp_f32_e32 v166, v80
	v_exp_f32_e32 v167, v64
	v_exp_f32_e32 v0, v81
	v_exp_f32_e32 v2, v65
	v_exp_f32_e32 v168, v66
	v_add_f32_e32 v3, v167, v166
	v_exp_f32_e32 v10, v71
	v_pk_add_f32 v[4:5], v[2:3], v[0:1]
	v_exp_f32_e32 v3, v82
	v_pk_add_f32 v[80:81], v[4:5], v[4:5] op_sel_hi:[0,1]
	v_exp_f32_e32 v80, v83
	v_exp_f32_e32 v4, v67
	v_add_f32_e32 v5, v168, v3
	v_pk_add_f32 v[6:7], v[4:5], v[80:81]
	s_nop 0
	v_pk_add_f32 v[82:83], v[6:7], v[6:7] op_sel_hi:[0,1]
	v_exp_f32_e32 v5, v84
	v_exp_f32_e32 v81, v68
	v_exp_f32_e32 v82, v85
	v_exp_f32_e32 v6, v69
	v_add_f32_e32 v7, v81, v5
	v_pk_add_f32 v[8:9], v[6:7], v[82:83]
	s_nop 0
	v_pk_add_f32 v[84:85], v[8:9], v[8:9] op_sel_hi:[0,1]
	v_exp_f32_e32 v7, v86
	v_exp_f32_e32 v83, v70
	v_exp_f32_e32 v84, v87
	v_add_f32_e32 v11, v83, v7
	v_pk_add_f32 v[8:9], v[10:11], v[84:85]
	v_exp_f32_e32 v11, v88
	v_pk_add_f32 v[86:87], v[8:9], v[8:9] op_sel_hi:[0,1]
	v_exp_f32_e32 v85, v72
	v_exp_f32_e32 v86, v89
	v_exp_f32_e32 v8, v73
	v_add_f32_e32 v9, v85, v11
	v_pk_add_f32 v[12:13], v[8:9], v[86:87]
	s_nop 0
	v_pk_add_f32 v[88:89], v[12:13], v[12:13] op_sel_hi:[0,1]
	v_exp_f32_e32 v9, v90
	v_exp_f32_e32 v87, v74
	v_exp_f32_e32 v88, v91
	v_exp_f32_e32 v12, v75
	v_add_f32_e32 v13, v87, v9
	v_pk_add_f32 v[14:15], v[12:13], v[88:89]
	s_nop 0
	v_pk_add_f32 v[74:75], v[14:15], v[14:15] op_sel_hi:[0,1]
	v_exp_f32_e32 v13, v92
	v_exp_f32_e32 v89, v76
	v_exp_f32_e32 v74, v93
	v_exp_f32_e32 v14, v77
	v_add_f32_e32 v15, v89, v13
	v_pk_add_f32 v[64:65], v[14:15], v[74:75]
	s_nop 0
	v_pk_add_f32 v[76:77], v[64:65], v[64:65] op_sel_hi:[0,1]
	v_exp_f32_e32 v15, v94
	v_exp_f32_e32 v75, v78
	v_exp_f32_e32 v76, v95
	v_exp_f32_e32 v64, v79
	v_add_f32_e32 v65, v75, v15
	v_pk_add_f32 v[66:67], v[64:65], v[76:77]
	s_nop 0
	v_pk_add_f32 v[66:67], v[66:67], v[66:67] op_sel:[0,1] op_sel_hi:[1,0]
	s_nop 0
	v_mov_b32_e32 v65, v66
	s_nop 1
	v_permlane32_swap_b32_e32 v66, v65
	v_add_f32_e32 v65, v66, v65
	v_cvt_pk_bf16_f32 v66, v166, v0
	v_cvt_pk_bf16_f32 v67, v3, v80
	v_cvt_pk_bf16_f32 v68, v5, v82
	v_cvt_pk_bf16_f32 v69, v7, v84
	s_waitcnt lgkmcnt(0)
	v_mfma_f32_32x32x16_bf16 v[32:47], v[212:215], v[66:69], v[32:47]
	v_add_f32_e32 v163, v163, v65
	s_waitcnt lgkmcnt(0)
	v_mfma_f32_32x32x16_bf16 v[16:31], v[216:219], v[66:69], v[16:31]
	v_cvt_pk_bf16_f32 v66, v11, v86
	v_cvt_pk_bf16_f32 v67, v9, v88
	v_cvt_pk_bf16_f32 v68, v13, v74
	v_cvt_pk_bf16_f32 v69, v15, v76
	s_waitcnt lgkmcnt(0)
	v_mfma_f32_32x32x16_bf16 v[32:47], v[220:223], v[66:69], v[32:47]
	v_cvt_pk_bf16_f32 v2, v167, v2
	v_cvt_pk_bf16_f32 v3, v168, v4
	v_cvt_pk_bf16_f32 v4, v81, v6
	v_cvt_pk_bf16_f32 v5, v83, v10
	s_waitcnt lgkmcnt(0)
	v_mfma_f32_32x32x16_bf16 v[16:31], v[224:227], v[66:69], v[16:31]
	s_waitcnt lgkmcnt(0)
	v_mfma_f32_32x32x16_bf16 v[32:47], v[228:231], v[2:5], v[32:47]
	s_waitcnt lgkmcnt(0)
	v_mfma_f32_32x32x16_bf16 v[16:31], v[232:235], v[2:5], v[16:31]
	v_cvt_pk_bf16_f32 v2, v85, v8
	v_cvt_pk_bf16_f32 v3, v87, v12
	v_cvt_pk_bf16_f32 v4, v89, v14
	v_cvt_pk_bf16_f32 v5, v75, v64
	s_waitcnt lgkmcnt(0)
	v_mfma_f32_32x32x16_bf16 v[32:47], v[236:239], v[2:5], v[32:47]
	s_waitcnt lgkmcnt(0)
	v_mfma_f32_32x32x16_bf16 v[16:31], v[240:243], v[2:5], v[16:31]

.LBB0_809:
	ds_read_b128 v[180:183], v161 offset:4608
	ds_read_b128 v[184:187], v161 offset:4624
	ds_read_b128 v[188:191], v161 offset:4640
	ds_read_b128 v[192:195], v161 offset:4656
	ds_read_b128 v[196:199], v161
	ds_read_b128 v[200:203], v161 offset:16
	ds_read_b128 v[204:207], v161 offset:32
	ds_read_b128 v[208:211], v161 offset:48
	s_cmp_lg_u32 s16, 0
	s_cselect_b64 s[6:7], -1, 0
	s_cmp_eq_u32 s16, 0
	s_waitcnt lgkmcnt(7)
	v_mfma_f32_32x32x16_bf16 v[64:79], v[180:183], v[96:99], v[48:63]
	s_waitcnt lgkmcnt(6)
	v_mfma_f32_32x32x16_bf16 v[64:79], v[184:187], v[100:103], v[64:79]
	s_waitcnt lgkmcnt(5)
	v_mfma_f32_32x32x16_bf16 v[64:79], v[188:191], v[104:107], v[64:79]
	s_waitcnt lgkmcnt(4)
	v_mfma_f32_32x32x16_bf16 v[64:79], v[192:195], v[108:111], v[64:79]
	s_waitcnt lgkmcnt(3)
	v_mfma_f32_32x32x16_bf16 v[80:95], v[196:199], v[96:99], v[48:63]
	s_waitcnt lgkmcnt(2)
	v_mfma_f32_32x32x16_bf16 v[80:95], v[200:203], v[100:103], v[80:95]
	s_waitcnt lgkmcnt(1)
	v_mfma_f32_32x32x16_bf16 v[80:95], v[204:207], v[104:107], v[80:95]
	s_waitcnt lgkmcnt(0)
	v_mfma_f32_32x32x16_bf16 v[80:95], v[208:211], v[108:111], v[80:95]
	ds_read_b64_tr_b16 v[212:213], v162 offset:9216
	ds_read_b64_tr_b16 v[214:215], v162 offset:10368
	ds_read_b64_tr_b16 v[216:217], v162 offset:9280
	ds_read_b64_tr_b16 v[218:219], v162 offset:10432
	ds_read_b64_tr_b16 v[220:221], v162 offset:11520
	ds_read_b64_tr_b16 v[222:223], v162 offset:12672
	ds_read_b64_tr_b16 v[224:225], v162 offset:11584
	ds_read_b64_tr_b16 v[226:227], v162 offset:12736
	ds_read_b64_tr_b16 v[228:229], v162 offset:13824
	ds_read_b64_tr_b16 v[230:231], v162 offset:14976
	ds_read_b64_tr_b16 v[232:233], v162 offset:13888
	ds_read_b64_tr_b16 v[234:235], v162 offset:15040
	ds_read_b64_tr_b16 v[236:237], v162 offset:16128
	ds_read_b64_tr_b16 v[238:239], v162 offset:17280
	ds_read_b64_tr_b16 v[240:241], v162 offset:16192
	ds_read_b64_tr_b16 v[242:243], v162 offset:17344
	s_cbranch_scc1 .LBB0_814
	s_add_i32 s2, s16, s15
	s_lshl_b32 s2, s2, 6
	s_sub_i32 s2, s2, s5
	s_add_i32 s19, s2, 0xffffff00
	s_cmpk_gt_i32 s2, 0x9f
	v_add_u32_e32 v0, s19, v159
	s_cbranch_scc1 .LBB0_812
	v_cmp_lt_i32_e32 vcc, s48, v0
	s_movk_i32 s19, 0xff5c
	s_nop 1
	v_cndmask_b32_e32 v80, v252, v80, vcc
	v_cmp_lt_i32_e32 vcc, s49, v0
	s_nop 1
	v_cndmask_b32_e32 v64, v252, v64, vcc
	v_cmp_lt_i32_e32 vcc, s66, v0
	s_nop 1
	v_cndmask_b32_e32 v81, v252, v81, vcc
	v_cmp_lt_i32_e32 vcc, s86, v0
	s_nop 1
	v_cndmask_b32_e32 v65, v252, v65, vcc
	v_cmp_lt_i32_e32 vcc, s87, v0
	s_nop 1
	v_cndmask_b32_e32 v82, v252, v82, vcc
	v_cmp_lt_i32_e32 vcc, s65, v0
	s_nop 1
	v_cndmask_b32_e32 v66, v252, v66, vcc
	v_cmp_lt_i32_e32 vcc, s64, v0
	s_nop 1
	v_cndmask_b32_e32 v83, v252, v83, vcc
	v_cmp_lt_i32_e32 vcc, s19, v0
	s_movk_i32 s19, 0xff77
	s_nop 0
	v_cndmask_b32_e32 v67, v252, v67, vcc
	v_cmp_lt_i32_e32 vcc, s19, v0
	s_movk_i32 s19, 0xff57
	s_nop 0
	v_cndmask_b32_e32 v84, v252, v84, vcc
	v_cmp_lt_i32_e32 vcc, s19, v0
	s_movk_i32 s19, 0xff76
	s_nop 0
	v_cndmask_b32_e32 v68, v252, v68, vcc
	v_cmp_lt_i32_e32 vcc, s19, v0
	s_movk_i32 s19, 0xff56
	s_nop 0
	v_cndmask_b32_e32 v85, v252, v85, vcc
	v_cmp_lt_i32_e32 vcc, s19, v0
	s_movk_i32 s19, 0xff75
	s_nop 0
	v_cndmask_b32_e32 v69, v252, v69, vcc
	v_cmp_lt_i32_e32 vcc, s19, v0
	s_movk_i32 s19, 0xff55
	s_nop 0
	v_cndmask_b32_e32 v86, v252, v86, vcc
	v_cmp_lt_i32_e32 vcc, s19, v0
	s_movk_i32 s19, 0xff74
	s_nop 0
	v_cndmask_b32_e32 v70, v252, v70, vcc
	v_cmp_lt_i32_e32 vcc, s19, v0
	s_movk_i32 s19, 0xff54
	s_nop 0
	v_cndmask_b32_e32 v87, v252, v87, vcc
	v_cmp_lt_i32_e32 vcc, s19, v0
	s_movk_i32 s19, 0xff6f
	s_nop 0
	v_cndmask_b32_e32 v71, v252, v71, vcc
	v_cmp_lt_i32_e32 vcc, s19, v0
	s_movk_i32 s19, 0xff4f
	s_nop 0
	v_cndmask_b32_e32 v88, v252, v88, vcc
	v_cmp_lt_i32_e32 vcc, s19, v0
	s_movk_i32 s19, 0xff6e
	s_nop 0
	v_cndmask_b32_e32 v72, v252, v72, vcc
	v_cmp_lt_i32_e32 vcc, s19, v0
	s_movk_i32 s19, 0xff4e
	s_nop 0
	v_cndmask_b32_e32 v89, v252, v89, vcc
	v_cmp_lt_i32_e32 vcc, s19, v0
	s_movk_i32 s19, 0xff6d
	s_nop 0
	v_cndmask_b32_e32 v73, v252, v73, vcc
	v_cmp_lt_i32_e32 vcc, s19, v0
	s_movk_i32 s19, 0xff4d
	s_nop 0
	v_cndmask_b32_e32 v90, v252, v90, vcc
	v_cmp_lt_i32_e32 vcc, s19, v0
	s_movk_i32 s19, 0xff6c
	s_nop 0
	v_cndmask_b32_e32 v74, v252, v74, vcc
	v_cmp_lt_i32_e32 vcc, s19, v0
	s_movk_i32 s19, 0xff4c
	s_nop 0
	v_cndmask_b32_e32 v91, v252, v91, vcc
	v_cmp_lt_i32_e32 vcc, s19, v0
	s_movk_i32 s19, 0xff67
	s_nop 0
	v_cndmask_b32_e32 v75, v252, v75, vcc
	v_cmp_lt_i32_e32 vcc, s19, v0
	s_movk_i32 s19, 0xff47
	s_nop 0
	v_cndmask_b32_e32 v92, v252, v92, vcc
	v_cmp_lt_i32_e32 vcc, s19, v0
	s_movk_i32 s19, 0xff66
	s_nop 0
	v_cndmask_b32_e32 v76, v252, v76, vcc
	v_cmp_lt_i32_e32 vcc, s19, v0
	s_movk_i32 s19, 0xff46
	s_nop 0
	v_cndmask_b32_e32 v93, v252, v93, vcc
	v_cmp_lt_i32_e32 vcc, s19, v0
	s_movk_i32 s19, 0xff65
	s_nop 0
	v_cndmask_b32_e32 v77, v252, v77, vcc
	v_cmp_lt_i32_e32 vcc, s19, v0
	s_movk_i32 s19, 0xff45
	s_nop 0
	v_cndmask_b32_e32 v94, v252, v94, vcc
	v_cmp_lt_i32_e32 vcc, s19, v0
	s_movk_i32 s19, 0xff64
	s_nop 0
	v_cndmask_b32_e32 v78, v252, v78, vcc
	v_cmp_lt_i32_e32 vcc, s19, v0
	s_movk_i32 s19, 0xff44
	s_nop 0
	v_cndmask_b32_e32 v95, v252, v95, vcc
	v_cmp_lt_i32_e32 vcc, s19, v0
	s_nop 1
	v_cndmask_b32_e32 v79, v252, v79, vcc

.LBB0_816:
	v_exp_f32_e32 v166, v80
	v_exp_f32_e32 v167, v64
	v_exp_f32_e32 v0, v81
	v_exp_f32_e32 v2, v65
	v_exp_f32_e32 v168, v66
	v_add_f32_e32 v3, v167, v166
	v_exp_f32_e32 v8, v69
	v_pk_add_f32 v[4:5], v[2:3], v[0:1]
	v_exp_f32_e32 v3, v82
	v_pk_add_f32 v[80:81], v[4:5], v[4:5] op_sel_hi:[0,1]
	v_exp_f32_e32 v80, v83
	v_exp_f32_e32 v4, v67
	v_add_f32_e32 v5, v168, v3
	v_exp_f32_e32 v12, v71
	s_add_i32 s2, s16, 5
	v_pk_add_f32 v[6:7], v[4:5], v[80:81]
	v_exp_f32_e32 v5, v84
	v_pk_add_f32 v[82:83], v[6:7], v[6:7] op_sel_hi:[0,1]
	v_exp_f32_e32 v81, v68
	v_exp_f32_e32 v82, v85
	s_min_i32 s2, s2, s18
	s_add_i32 s2, s2, s15
	v_add_f32_e32 v9, v81, v5
	v_pk_add_f32 v[6:7], v[8:9], v[82:83]
	v_exp_f32_e32 v9, v86
	v_pk_add_f32 v[84:85], v[6:7], v[6:7] op_sel_hi:[0,1]
	v_exp_f32_e32 v83, v70
	v_exp_f32_e32 v84, v87
	v_add_f32_e32 v13, v83, v9
	v_pk_add_f32 v[6:7], v[12:13], v[84:85]
	v_exp_f32_e32 v13, v88
	v_pk_add_f32 v[86:87], v[6:7], v[6:7] op_sel_hi:[0,1]
	v_exp_f32_e32 v85, v72
	v_exp_f32_e32 v86, v89
	v_exp_f32_e32 v6, v73
	v_add_f32_e32 v7, v85, v13
	v_pk_add_f32 v[10:11], v[6:7], v[86:87]
	s_nop 0
	v_pk_add_f32 v[88:89], v[10:11], v[10:11] op_sel_hi:[0,1]
	v_exp_f32_e32 v7, v90
	v_exp_f32_e32 v87, v74
	v_exp_f32_e32 v88, v91
	v_exp_f32_e32 v10, v75
	v_add_f32_e32 v11, v87, v7
	v_pk_add_f32 v[14:15], v[10:11], v[88:89]
	s_nop 0
	v_pk_add_f32 v[74:75], v[14:15], v[14:15] op_sel_hi:[0,1]
	v_exp_f32_e32 v11, v92
	v_exp_f32_e32 v89, v76
	v_exp_f32_e32 v74, v93
	v_exp_f32_e32 v14, v77
	v_add_f32_e32 v15, v89, v11
	v_pk_add_f32 v[64:65], v[14:15], v[74:75]
	s_nop 0
	v_pk_add_f32 v[76:77], v[64:65], v[64:65] op_sel_hi:[0,1]
	v_exp_f32_e32 v15, v94
	v_exp_f32_e32 v75, v78
	v_exp_f32_e32 v76, v95
	v_exp_f32_e32 v64, v79
	v_add_f32_e32 v65, v75, v15
	v_pk_add_f32 v[66:67], v[64:65], v[76:77]
	s_nop 0
	v_pk_add_f32 v[66:67], v[66:67], v[66:67] op_sel:[0,1] op_sel_hi:[1,0]
	s_nop 0
	v_mov_b32_e32 v65, v66
	s_nop 1
	v_permlane32_swap_b32_e32 v66, v65
	v_add_f32_e32 v65, v66, v65
	v_cvt_pk_bf16_f32 v66, v166, v0
	v_cvt_pk_bf16_f32 v67, v3, v80
	v_cvt_pk_bf16_f32 v68, v5, v82
	v_cvt_pk_bf16_f32 v69, v9, v84
	s_waitcnt lgkmcnt(0)
	v_mfma_f32_32x32x16_bf16 v[32:47], v[212:215], v[66:69], v[32:47]
	v_lshl_add_u32 v0, s2, 6, v164
	s_or_b32 s2, s16, 1
	v_add_f32_e32 v163, v163, v65
	s_cmp_ge_u32 s2, s17
	s_waitcnt lgkmcnt(0)
	v_mfma_f32_32x32x16_bf16 v[16:31], v[216:219], v[66:69], v[16:31]
	v_cvt_pk_bf16_f32 v66, v13, v86
	v_cvt_pk_bf16_f32 v67, v7, v88
	v_cvt_pk_bf16_f32 v68, v11, v74
	v_cvt_pk_bf16_f32 v69, v15, v76
	s_waitcnt lgkmcnt(0)
	v_mfma_f32_32x32x16_bf16 v[32:47], v[220:223], v[66:69], v[32:47]
	v_cvt_pk_bf16_f32 v2, v167, v2
	v_cvt_pk_bf16_f32 v3, v168, v4
	v_cvt_pk_bf16_f32 v4, v81, v8
	v_cvt_pk_bf16_f32 v5, v83, v12
	s_waitcnt lgkmcnt(0)
	v_mfma_f32_32x32x16_bf16 v[16:31], v[224:227], v[66:69], v[16:31]
	s_waitcnt lgkmcnt(0)
	v_mfma_f32_32x32x16_bf16 v[32:47], v[228:231], v[2:5], v[32:47]
	s_waitcnt lgkmcnt(0)
	v_mfma_f32_32x32x16_bf16 v[16:31], v[232:235], v[2:5], v[16:31]
	v_cvt_pk_bf16_f32 v2, v85, v6
	v_cvt_pk_bf16_f32 v3, v87, v10
	v_cvt_pk_bf16_f32 v4, v89, v14
	v_cvt_pk_bf16_f32 v5, v75, v64
	s_waitcnt lgkmcnt(0)
	v_mfma_f32_32x32x16_bf16 v[32:47], v[236:239], v[2:5], v[32:47]
	s_waitcnt vmcnt(7)
	ds_write_b128 v160, v[112:115] offset:18432
	s_waitcnt vmcnt(6)
	ds_write_b128 v160, v[116:119] offset:27648
	s_waitcnt lgkmcnt(2)
	v_mfma_f32_32x32x16_bf16 v[16:31], v[240:243], v[2:5], v[16:31]
	v_mad_i64_i32 v[2:3], s[20:21], v0, s3, v[152:153]
	global_load_dwordx4 v[112:115], v[2:3], off offset:2048
	global_load_dwordx4 v[116:119], v[2:3], off offset:2560
	v_cndmask_b32_e64 v0, 0, 1, s[6:7]
	v_cmp_ne_u32_e64 s[6:7], 1, v0
	s_waitcnt lgkmcnt(0)
	s_barrier
	s_cbranch_scc1 .LBB0_825
	ds_read_b128 v[180:183], v161 offset:23040
	ds_read_b128 v[184:187], v161 offset:23056
	ds_read_b128 v[188:191], v161 offset:23072
	ds_read_b128 v[192:195], v161 offset:23088
	ds_read_b128 v[196:199], v161 offset:18432
	ds_read_b128 v[200:203], v161 offset:18448
	ds_read_b128 v[204:207], v161 offset:18464
	ds_read_b128 v[208:211], v161 offset:18480
	s_and_b64 vcc, exec, s[6:7]
	s_waitcnt lgkmcnt(7)
	v_mfma_f32_32x32x16_bf16 v[64:79], v[180:183], v[96:99], v[48:63]
	s_waitcnt lgkmcnt(6)
	v_mfma_f32_32x32x16_bf16 v[64:79], v[184:187], v[100:103], v[64:79]
	s_waitcnt lgkmcnt(5)
	v_mfma_f32_32x32x16_bf16 v[64:79], v[188:191], v[104:107], v[64:79]
	s_waitcnt lgkmcnt(4)
	v_mfma_f32_32x32x16_bf16 v[64:79], v[192:195], v[108:111], v[64:79]
	s_waitcnt lgkmcnt(3)
	v_mfma_f32_32x32x16_bf16 v[80:95], v[196:199], v[96:99], v[48:63]
	s_waitcnt lgkmcnt(2)
	v_mfma_f32_32x32x16_bf16 v[80:95], v[200:203], v[100:103], v[80:95]
	s_waitcnt lgkmcnt(1)
	v_mfma_f32_32x32x16_bf16 v[80:95], v[204:207], v[104:107], v[80:95]
	s_waitcnt lgkmcnt(0)
	v_mfma_f32_32x32x16_bf16 v[80:95], v[208:211], v[108:111], v[80:95]
	ds_read_b64_tr_b16 v[212:213], v162 offset:27648
	ds_read_b64_tr_b16 v[214:215], v162 offset:28800
	ds_read_b64_tr_b16 v[216:217], v162 offset:27712
	ds_read_b64_tr_b16 v[218:219], v162 offset:28864
	ds_read_b64_tr_b16 v[220:221], v162 offset:29952
	ds_read_b64_tr_b16 v[222:223], v162 offset:31104
	ds_read_b64_tr_b16 v[224:225], v162 offset:30016
	ds_read_b64_tr_b16 v[226:227], v162 offset:31168
	ds_read_b64_tr_b16 v[228:229], v162 offset:32256
	ds_read_b64_tr_b16 v[230:231], v162 offset:33408
	ds_read_b64_tr_b16 v[232:233], v162 offset:32320
	ds_read_b64_tr_b16 v[234:235], v162 offset:33472
	ds_read_b64_tr_b16 v[236:237], v162 offset:34560
	ds_read_b64_tr_b16 v[238:239], v162 offset:35712
	ds_read_b64_tr_b16 v[240:241], v162 offset:34624
	ds_read_b64_tr_b16 v[242:243], v162 offset:35776
	s_cbranch_vccnz .LBB0_822
	s_add_i32 s2, s2, s15
	s_lshl_b32 s2, s2, 6
	s_sub_i32 s2, s2, s5
	s_add_i32 s19, s2, 0xffffff00
	s_cmpk_gt_i32 s2, 0x9f
	v_add_u32_e32 v0, s19, v159
	s_cbranch_scc1 .LBB0_820
	v_cmp_lt_i32_e32 vcc, s48, v0
	s_movk_i32 s19, 0xff5c
	s_nop 1
	v_cndmask_b32_e32 v80, v252, v80, vcc
	v_cmp_lt_i32_e32 vcc, s49, v0
	s_nop 1
	v_cndmask_b32_e32 v64, v252, v64, vcc
	v_cmp_lt_i32_e32 vcc, s66, v0
	s_nop 1
	v_cndmask_b32_e32 v81, v252, v81, vcc
	v_cmp_lt_i32_e32 vcc, s86, v0
	s_nop 1
	v_cndmask_b32_e32 v65, v252, v65, vcc
	v_cmp_lt_i32_e32 vcc, s87, v0
	s_nop 1
	v_cndmask_b32_e32 v82, v252, v82, vcc
	v_cmp_lt_i32_e32 vcc, s65, v0
	s_nop 1
	v_cndmask_b32_e32 v66, v252, v66, vcc
	v_cmp_lt_i32_e32 vcc, s64, v0
	s_nop 1
	v_cndmask_b32_e32 v83, v252, v83, vcc
	v_cmp_lt_i32_e32 vcc, s19, v0
	s_movk_i32 s19, 0xff77
	s_nop 0
	v_cndmask_b32_e32 v67, v252, v67, vcc
	v_cmp_lt_i32_e32 vcc, s19, v0
	s_movk_i32 s19, 0xff57
	s_nop 0
	v_cndmask_b32_e32 v84, v252, v84, vcc
	v_cmp_lt_i32_e32 vcc, s19, v0
	s_movk_i32 s19, 0xff76
	s_nop 0
	v_cndmask_b32_e32 v68, v252, v68, vcc
	v_cmp_lt_i32_e32 vcc, s19, v0
	s_movk_i32 s19, 0xff56
	s_nop 0
	v_cndmask_b32_e32 v85, v252, v85, vcc
	v_cmp_lt_i32_e32 vcc, s19, v0
	s_movk_i32 s19, 0xff75
	s_nop 0
	v_cndmask_b32_e32 v69, v252, v69, vcc
	v_cmp_lt_i32_e32 vcc, s19, v0
	s_movk_i32 s19, 0xff55
	s_nop 0
	v_cndmask_b32_e32 v86, v252, v86, vcc
	v_cmp_lt_i32_e32 vcc, s19, v0
	s_movk_i32 s19, 0xff74
	s_nop 0
	v_cndmask_b32_e32 v70, v252, v70, vcc
	v_cmp_lt_i32_e32 vcc, s19, v0
	s_movk_i32 s19, 0xff54
	s_nop 0
	v_cndmask_b32_e32 v87, v252, v87, vcc
	v_cmp_lt_i32_e32 vcc, s19, v0
	s_movk_i32 s19, 0xff6f
	s_nop 0
	v_cndmask_b32_e32 v71, v252, v71, vcc
	v_cmp_lt_i32_e32 vcc, s19, v0
	s_movk_i32 s19, 0xff4f
	s_nop 0
	v_cndmask_b32_e32 v88, v252, v88, vcc
	v_cmp_lt_i32_e32 vcc, s19, v0
	s_movk_i32 s19, 0xff6e
	s_nop 0
	v_cndmask_b32_e32 v72, v252, v72, vcc
	v_cmp_lt_i32_e32 vcc, s19, v0
	s_movk_i32 s19, 0xff4e
	s_nop 0
	v_cndmask_b32_e32 v89, v252, v89, vcc
	v_cmp_lt_i32_e32 vcc, s19, v0
	s_movk_i32 s19, 0xff6d
	s_nop 0
	v_cndmask_b32_e32 v73, v252, v73, vcc
	v_cmp_lt_i32_e32 vcc, s19, v0
	s_movk_i32 s19, 0xff4d
	s_nop 0
	v_cndmask_b32_e32 v90, v252, v90, vcc
	v_cmp_lt_i32_e32 vcc, s19, v0
	s_movk_i32 s19, 0xff6c
	s_nop 0
	v_cndmask_b32_e32 v74, v252, v74, vcc
	v_cmp_lt_i32_e32 vcc, s19, v0
	s_movk_i32 s19, 0xff4c
	s_nop 0
	v_cndmask_b32_e32 v91, v252, v91, vcc
	v_cmp_lt_i32_e32 vcc, s19, v0
	s_movk_i32 s19, 0xff67
	s_nop 0
	v_cndmask_b32_e32 v75, v252, v75, vcc
	v_cmp_lt_i32_e32 vcc, s19, v0
	s_movk_i32 s19, 0xff47
	s_nop 0
	v_cndmask_b32_e32 v92, v252, v92, vcc
	v_cmp_lt_i32_e32 vcc, s19, v0
	s_movk_i32 s19, 0xff66
	s_nop 0
	v_cndmask_b32_e32 v76, v252, v76, vcc
	v_cmp_lt_i32_e32 vcc, s19, v0
	s_movk_i32 s19, 0xff46
	s_nop 0
	v_cndmask_b32_e32 v93, v252, v93, vcc
	v_cmp_lt_i32_e32 vcc, s19, v0
	s_movk_i32 s19, 0xff65
	s_nop 0
	v_cndmask_b32_e32 v77, v252, v77, vcc
	v_cmp_lt_i32_e32 vcc, s19, v0
	s_movk_i32 s19, 0xff45
	s_nop 0
	v_cndmask_b32_e32 v94, v252, v94, vcc
	v_cmp_lt_i32_e32 vcc, s19, v0
	s_movk_i32 s19, 0xff64
	s_nop 0
	v_cndmask_b32_e32 v78, v252, v78, vcc
	v_cmp_lt_i32_e32 vcc, s19, v0
	s_movk_i32 s19, 0xff44
	s_nop 0
	v_cndmask_b32_e32 v95, v252, v95, vcc
	v_cmp_lt_i32_e32 vcc, s19, v0
	s_nop 1
	v_cndmask_b32_e32 v79, v252, v79, vcc

.LBB0_825:
	s_add_i32 s2, s16, 6
	s_min_i32 s2, s2, s18
	s_add_i32 s2, s2, s15
	v_lshl_add_u32 v0, s2, 6, v164
	s_waitcnt vmcnt(7)
	ds_write_b128 v160, v[120:123]
	s_waitcnt vmcnt(6)
	ds_write_b128 v160, v[124:127] offset:9216
	v_mad_i64_i32 v[2:3], s[20:21], v0, s3, v[152:153]
	global_load_dwordx4 v[120:123], v[2:3], off offset:2048
	global_load_dwordx4 v[124:127], v[2:3], off offset:2560
	s_or_b32 s2, s16, 2
	s_cmp_ge_u32 s2, s17
	s_waitcnt lgkmcnt(0)
	s_barrier
	s_cbranch_scc1 .LBB0_834
	ds_read_b128 v[180:183], v161 offset:4608
	ds_read_b128 v[184:187], v161 offset:4624
	ds_read_b128 v[188:191], v161 offset:4640
	ds_read_b128 v[192:195], v161 offset:4656
	ds_read_b128 v[196:199], v161
	ds_read_b128 v[200:203], v161 offset:16
	ds_read_b128 v[204:207], v161 offset:32
	ds_read_b128 v[208:211], v161 offset:48
	s_and_b64 vcc, exec, s[6:7]
	s_waitcnt lgkmcnt(7)
	v_mfma_f32_32x32x16_bf16 v[64:79], v[180:183], v[96:99], v[48:63]
	s_waitcnt lgkmcnt(6)
	v_mfma_f32_32x32x16_bf16 v[64:79], v[184:187], v[100:103], v[64:79]
	s_waitcnt lgkmcnt(5)
	v_mfma_f32_32x32x16_bf16 v[64:79], v[188:191], v[104:107], v[64:79]
	s_waitcnt lgkmcnt(4)
	v_mfma_f32_32x32x16_bf16 v[64:79], v[192:195], v[108:111], v[64:79]
	s_waitcnt lgkmcnt(3)
	v_mfma_f32_32x32x16_bf16 v[80:95], v[196:199], v[96:99], v[48:63]
	s_waitcnt lgkmcnt(2)
	v_mfma_f32_32x32x16_bf16 v[80:95], v[200:203], v[100:103], v[80:95]
	s_waitcnt lgkmcnt(1)
	v_mfma_f32_32x32x16_bf16 v[80:95], v[204:207], v[104:107], v[80:95]
	s_waitcnt lgkmcnt(0)
	v_mfma_f32_32x32x16_bf16 v[80:95], v[208:211], v[108:111], v[80:95]
	ds_read_b64_tr_b16 v[212:213], v162 offset:9216
	ds_read_b64_tr_b16 v[214:215], v162 offset:10368
	ds_read_b64_tr_b16 v[216:217], v162 offset:9280
	ds_read_b64_tr_b16 v[218:219], v162 offset:10432
	ds_read_b64_tr_b16 v[220:221], v162 offset:11520
	ds_read_b64_tr_b16 v[222:223], v162 offset:12672
	ds_read_b64_tr_b16 v[224:225], v162 offset:11584
	ds_read_b64_tr_b16 v[226:227], v162 offset:12736
	ds_read_b64_tr_b16 v[228:229], v162 offset:13824
	ds_read_b64_tr_b16 v[230:231], v162 offset:14976
	ds_read_b64_tr_b16 v[232:233], v162 offset:13888
	ds_read_b64_tr_b16 v[234:235], v162 offset:15040
	ds_read_b64_tr_b16 v[236:237], v162 offset:16128
	ds_read_b64_tr_b16 v[238:239], v162 offset:17280
	ds_read_b64_tr_b16 v[240:241], v162 offset:16192
	ds_read_b64_tr_b16 v[242:243], v162 offset:17344
	s_cbranch_vccnz .LBB0_831
	s_add_i32 s2, s2, s15
	s_lshl_b32 s2, s2, 6
	s_sub_i32 s2, s2, s5
	s_add_i32 s19, s2, 0xffffff00
	s_cmpk_gt_i32 s2, 0x9f
	v_add_u32_e32 v0, s19, v159
	s_cbranch_scc1 .LBB0_829
	v_cmp_lt_i32_e32 vcc, s48, v0
	s_movk_i32 s19, 0xff5c
	s_nop 1
	v_cndmask_b32_e32 v80, v252, v80, vcc
	v_cmp_lt_i32_e32 vcc, s49, v0
	s_nop 1
	v_cndmask_b32_e32 v64, v252, v64, vcc
	v_cmp_lt_i32_e32 vcc, s66, v0
	s_nop 1
	v_cndmask_b32_e32 v81, v252, v81, vcc
	v_cmp_lt_i32_e32 vcc, s86, v0
	s_nop 1
	v_cndmask_b32_e32 v65, v252, v65, vcc
	v_cmp_lt_i32_e32 vcc, s87, v0
	s_nop 1
	v_cndmask_b32_e32 v82, v252, v82, vcc
	v_cmp_lt_i32_e32 vcc, s65, v0
	s_nop 1
	v_cndmask_b32_e32 v66, v252, v66, vcc
	v_cmp_lt_i32_e32 vcc, s64, v0
	s_nop 1
	v_cndmask_b32_e32 v83, v252, v83, vcc
	v_cmp_lt_i32_e32 vcc, s19, v0
	s_movk_i32 s19, 0xff77
	s_nop 0
	v_cndmask_b32_e32 v67, v252, v67, vcc
	v_cmp_lt_i32_e32 vcc, s19, v0
	s_movk_i32 s19, 0xff57
	s_nop 0
	v_cndmask_b32_e32 v84, v252, v84, vcc
	v_cmp_lt_i32_e32 vcc, s19, v0
	s_movk_i32 s19, 0xff76
	s_nop 0
	v_cndmask_b32_e32 v68, v252, v68, vcc
	v_cmp_lt_i32_e32 vcc, s19, v0
	s_movk_i32 s19, 0xff56
	s_nop 0
	v_cndmask_b32_e32 v85, v252, v85, vcc
	v_cmp_lt_i32_e32 vcc, s19, v0
	s_movk_i32 s19, 0xff75
	s_nop 0
	v_cndmask_b32_e32 v69, v252, v69, vcc
	v_cmp_lt_i32_e32 vcc, s19, v0
	s_movk_i32 s19, 0xff55
	s_nop 0
	v_cndmask_b32_e32 v86, v252, v86, vcc
	v_cmp_lt_i32_e32 vcc, s19, v0
	s_movk_i32 s19, 0xff74
	s_nop 0
	v_cndmask_b32_e32 v70, v252, v70, vcc
	v_cmp_lt_i32_e32 vcc, s19, v0
	s_movk_i32 s19, 0xff54
	s_nop 0
	v_cndmask_b32_e32 v87, v252, v87, vcc
	v_cmp_lt_i32_e32 vcc, s19, v0
	s_movk_i32 s19, 0xff6f
	s_nop 0
	v_cndmask_b32_e32 v71, v252, v71, vcc
	v_cmp_lt_i32_e32 vcc, s19, v0
	s_movk_i32 s19, 0xff4f
	s_nop 0
	v_cndmask_b32_e32 v88, v252, v88, vcc
	v_cmp_lt_i32_e32 vcc, s19, v0
	s_movk_i32 s19, 0xff6e
	s_nop 0
	v_cndmask_b32_e32 v72, v252, v72, vcc
	v_cmp_lt_i32_e32 vcc, s19, v0
	s_movk_i32 s19, 0xff4e
	s_nop 0
	v_cndmask_b32_e32 v89, v252, v89, vcc
	v_cmp_lt_i32_e32 vcc, s19, v0
	s_movk_i32 s19, 0xff6d
	s_nop 0
	v_cndmask_b32_e32 v73, v252, v73, vcc
	v_cmp_lt_i32_e32 vcc, s19, v0
	s_movk_i32 s19, 0xff4d
	s_nop 0
	v_cndmask_b32_e32 v90, v252, v90, vcc
	v_cmp_lt_i32_e32 vcc, s19, v0
	s_movk_i32 s19, 0xff6c
	s_nop 0
	v_cndmask_b32_e32 v74, v252, v74, vcc
	v_cmp_lt_i32_e32 vcc, s19, v0
	s_movk_i32 s19, 0xff4c
	s_nop 0
	v_cndmask_b32_e32 v91, v252, v91, vcc
	v_cmp_lt_i32_e32 vcc, s19, v0
	s_movk_i32 s19, 0xff67
	s_nop 0
	v_cndmask_b32_e32 v75, v252, v75, vcc
	v_cmp_lt_i32_e32 vcc, s19, v0
	s_movk_i32 s19, 0xff47
	s_nop 0
	v_cndmask_b32_e32 v92, v252, v92, vcc
	v_cmp_lt_i32_e32 vcc, s19, v0
	s_movk_i32 s19, 0xff66
	s_nop 0
	v_cndmask_b32_e32 v76, v252, v76, vcc
	v_cmp_lt_i32_e32 vcc, s19, v0
	s_movk_i32 s19, 0xff46
	s_nop 0
	v_cndmask_b32_e32 v93, v252, v93, vcc
	v_cmp_lt_i32_e32 vcc, s19, v0
	s_movk_i32 s19, 0xff65
	s_nop 0
	v_cndmask_b32_e32 v77, v252, v77, vcc
	v_cmp_lt_i32_e32 vcc, s19, v0
	s_movk_i32 s19, 0xff45
	s_nop 0
	v_cndmask_b32_e32 v94, v252, v94, vcc
	v_cmp_lt_i32_e32 vcc, s19, v0
	s_movk_i32 s19, 0xff64
	s_nop 0
	v_cndmask_b32_e32 v78, v252, v78, vcc
	v_cmp_lt_i32_e32 vcc, s19, v0
	s_movk_i32 s19, 0xff44
	s_nop 0
	v_cndmask_b32_e32 v95, v252, v95, vcc
	v_cmp_lt_i32_e32 vcc, s19, v0
	s_nop 1
	v_cndmask_b32_e32 v79, v252, v79, vcc

.LBB0_833:
	v_exp_f32_e32 v166, v80
	v_exp_f32_e32 v167, v64
	v_exp_f32_e32 v0, v81
	v_exp_f32_e32 v2, v65
	v_exp_f32_e32 v168, v66
	v_add_f32_e32 v3, v167, v166
	v_exp_f32_e32 v8, v69
	v_pk_add_f32 v[4:5], v[2:3], v[0:1]
	v_exp_f32_e32 v3, v82
	v_pk_add_f32 v[80:81], v[4:5], v[4:5] op_sel_hi:[0,1]
	v_exp_f32_e32 v80, v83
	v_exp_f32_e32 v4, v67
	v_add_f32_e32 v5, v168, v3
	v_exp_f32_e32 v12, v71
	v_pk_add_f32 v[6:7], v[4:5], v[80:81]
	s_nop 0
	v_pk_add_f32 v[82:83], v[6:7], v[6:7] op_sel_hi:[0,1]
	v_exp_f32_e32 v5, v84
	v_exp_f32_e32 v81, v68
	v_exp_f32_e32 v82, v85
	v_add_f32_e32 v9, v81, v5
	v_pk_add_f32 v[6:7], v[8:9], v[82:83]
	v_exp_f32_e32 v9, v86
	v_pk_add_f32 v[84:85], v[6:7], v[6:7] op_sel_hi:[0,1]
	v_exp_f32_e32 v83, v70
	v_exp_f32_e32 v84, v87
	v_add_f32_e32 v13, v83, v9
	v_pk_add_f32 v[6:7], v[12:13], v[84:85]
	v_exp_f32_e32 v13, v88
	v_pk_add_f32 v[86:87], v[6:7], v[6:7] op_sel_hi:[0,1]
	v_exp_f32_e32 v85, v72
	v_exp_f32_e32 v86, v89
	v_exp_f32_e32 v6, v73
	v_add_f32_e32 v7, v85, v13
	v_pk_add_f32 v[10:11], v[6:7], v[86:87]
	s_nop 0
	v_pk_add_f32 v[88:89], v[10:11], v[10:11] op_sel_hi:[0,1]
	v_exp_f32_e32 v7, v90
	v_exp_f32_e32 v87, v74
	v_exp_f32_e32 v88, v91
	v_exp_f32_e32 v10, v75
	v_add_f32_e32 v11, v87, v7
	v_pk_add_f32 v[14:15], v[10:11], v[88:89]
	s_nop 0
	v_pk_add_f32 v[74:75], v[14:15], v[14:15] op_sel_hi:[0,1]
	v_exp_f32_e32 v11, v92
	v_exp_f32_e32 v89, v76
	v_exp_f32_e32 v74, v93
	v_exp_f32_e32 v14, v77
	v_add_f32_e32 v15, v89, v11
	v_pk_add_f32 v[64:65], v[14:15], v[74:75]
	s_nop 0
	v_pk_add_f32 v[76:77], v[64:65], v[64:65] op_sel_hi:[0,1]
	v_exp_f32_e32 v15, v94
	v_exp_f32_e32 v75, v78
	v_exp_f32_e32 v76, v95
	v_exp_f32_e32 v64, v79
	v_add_f32_e32 v65, v75, v15
	v_pk_add_f32 v[66:67], v[64:65], v[76:77]
	s_nop 0
	v_pk_add_f32 v[66:67], v[66:67], v[66:67] op_sel:[0,1] op_sel_hi:[1,0]
	s_nop 0
	v_mov_b32_e32 v65, v66
	s_nop 1
	v_permlane32_swap_b32_e32 v66, v65
	v_add_f32_e32 v65, v66, v65
	v_cvt_pk_bf16_f32 v66, v166, v0
	v_cvt_pk_bf16_f32 v67, v3, v80
	v_cvt_pk_bf16_f32 v68, v5, v82
	v_cvt_pk_bf16_f32 v69, v9, v84
	s_waitcnt lgkmcnt(0)
	v_mfma_f32_32x32x16_bf16 v[32:47], v[212:215], v[66:69], v[32:47]
	v_add_f32_e32 v163, v163, v65
	s_waitcnt lgkmcnt(0)
	v_mfma_f32_32x32x16_bf16 v[16:31], v[216:219], v[66:69], v[16:31]
	v_cvt_pk_bf16_f32 v66, v13, v86
	v_cvt_pk_bf16_f32 v67, v7, v88
	v_cvt_pk_bf16_f32 v68, v11, v74
	v_cvt_pk_bf16_f32 v69, v15, v76
	s_waitcnt lgkmcnt(0)
	v_mfma_f32_32x32x16_bf16 v[32:47], v[220:223], v[66:69], v[32:47]
	v_cvt_pk_bf16_f32 v2, v167, v2
	v_cvt_pk_bf16_f32 v3, v168, v4
	v_cvt_pk_bf16_f32 v4, v81, v8
	v_cvt_pk_bf16_f32 v5, v83, v12
	s_waitcnt lgkmcnt(0)
	v_mfma_f32_32x32x16_bf16 v[16:31], v[224:227], v[66:69], v[16:31]
	s_waitcnt lgkmcnt(0)
	v_mfma_f32_32x32x16_bf16 v[32:47], v[228:231], v[2:5], v[32:47]
	s_waitcnt lgkmcnt(0)
	v_mfma_f32_32x32x16_bf16 v[16:31], v[232:235], v[2:5], v[16:31]
	v_cvt_pk_bf16_f32 v2, v85, v6
	v_cvt_pk_bf16_f32 v3, v87, v10
	v_cvt_pk_bf16_f32 v4, v89, v14
	v_cvt_pk_bf16_f32 v5, v75, v64
	s_waitcnt lgkmcnt(0)
	v_mfma_f32_32x32x16_bf16 v[32:47], v[236:239], v[2:5], v[32:47]
	s_waitcnt lgkmcnt(0)
	v_mfma_f32_32x32x16_bf16 v[16:31], v[240:243], v[2:5], v[16:31]
.LBB0_834:
	s_add_i32 s2, s16, 7
	s_min_i32 s2, s2, s18
	s_add_i32 s2, s2, s15
	v_lshl_add_u32 v0, s2, 6, v164
	s_waitcnt vmcnt(7)
	ds_write_b128 v160, v[128:131] offset:18432
	s_waitcnt vmcnt(6)
	ds_write_b128 v160, v[132:135] offset:27648
	v_mad_i64_i32 v[2:3], s[20:21], v0, s3, v[152:153]
	global_load_dwordx4 v[128:131], v[2:3], off offset:2048
	global_load_dwordx4 v[132:135], v[2:3], off offset:2560
	s_or_b32 s2, s16, 3
	s_cmp_ge_u32 s2, s17
	s_waitcnt lgkmcnt(0)
	s_barrier
	s_cbranch_scc1 .LBB0_808
	ds_read_b128 v[180:183], v161 offset:23040
	ds_read_b128 v[184:187], v161 offset:23056
	ds_read_b128 v[188:191], v161 offset:23072
	ds_read_b128 v[192:195], v161 offset:23088
	ds_read_b128 v[196:199], v161 offset:18432
	ds_read_b128 v[200:203], v161 offset:18448
	ds_read_b128 v[204:207], v161 offset:18464
	ds_read_b128 v[208:211], v161 offset:18480
	s_and_b64 vcc, exec, s[6:7]
	s_waitcnt lgkmcnt(7)
	v_mfma_f32_32x32x16_bf16 v[64:79], v[180:183], v[96:99], v[48:63]
	s_waitcnt lgkmcnt(6)
	v_mfma_f32_32x32x16_bf16 v[64:79], v[184:187], v[100:103], v[64:79]
	s_waitcnt lgkmcnt(5)
	v_mfma_f32_32x32x16_bf16 v[64:79], v[188:191], v[104:107], v[64:79]
	s_waitcnt lgkmcnt(4)
	v_mfma_f32_32x32x16_bf16 v[64:79], v[192:195], v[108:111], v[64:79]
	s_waitcnt lgkmcnt(3)
	v_mfma_f32_32x32x16_bf16 v[80:95], v[196:199], v[96:99], v[48:63]
	s_waitcnt lgkmcnt(2)
	v_mfma_f32_32x32x16_bf16 v[80:95], v[200:203], v[100:103], v[80:95]
	s_waitcnt lgkmcnt(1)
	v_mfma_f32_32x32x16_bf16 v[80:95], v[204:207], v[104:107], v[80:95]
	s_waitcnt lgkmcnt(0)
	v_mfma_f32_32x32x16_bf16 v[80:95], v[208:211], v[108:111], v[80:95]
	ds_read_b64_tr_b16 v[212:213], v162 offset:27648
	ds_read_b64_tr_b16 v[214:215], v162 offset:28800
	ds_read_b64_tr_b16 v[216:217], v162 offset:27712
	ds_read_b64_tr_b16 v[218:219], v162 offset:28864
	ds_read_b64_tr_b16 v[220:221], v162 offset:29952
	ds_read_b64_tr_b16 v[222:223], v162 offset:31104
	ds_read_b64_tr_b16 v[224:225], v162 offset:30016
	ds_read_b64_tr_b16 v[226:227], v162 offset:31168
	ds_read_b64_tr_b16 v[228:229], v162 offset:32256
	ds_read_b64_tr_b16 v[230:231], v162 offset:33408
	ds_read_b64_tr_b16 v[232:233], v162 offset:32320
	ds_read_b64_tr_b16 v[234:235], v162 offset:33472
	ds_read_b64_tr_b16 v[236:237], v162 offset:34560
	ds_read_b64_tr_b16 v[238:239], v162 offset:35712
	ds_read_b64_tr_b16 v[240:241], v162 offset:34624
	ds_read_b64_tr_b16 v[242:243], v162 offset:35776
	s_cbranch_vccnz .LBB0_840
	s_add_i32 s2, s2, s15
	s_lshl_b32 s2, s2, 6
	s_sub_i32 s2, s2, s5
	s_add_i32 s6, s2, 0xffffff00
	s_cmpk_gt_i32 s2, 0x9f
	v_add_u32_e32 v0, s6, v159
	s_cbranch_scc1 .LBB0_838
	v_cmp_lt_i32_e32 vcc, s48, v0
	s_movk_i32 s6, 0xff5c
	s_nop 1
	v_cndmask_b32_e32 v80, v252, v80, vcc
	v_cmp_lt_i32_e32 vcc, s49, v0
	s_nop 1
	v_cndmask_b32_e32 v64, v252, v64, vcc
	v_cmp_lt_i32_e32 vcc, s66, v0
	s_nop 1
	v_cndmask_b32_e32 v81, v252, v81, vcc
	v_cmp_lt_i32_e32 vcc, s86, v0
	s_nop 1
	v_cndmask_b32_e32 v65, v252, v65, vcc
	v_cmp_lt_i32_e32 vcc, s87, v0
	s_nop 1
	v_cndmask_b32_e32 v82, v252, v82, vcc
	v_cmp_lt_i32_e32 vcc, s65, v0
	s_nop 1
	v_cndmask_b32_e32 v66, v252, v66, vcc
	v_cmp_lt_i32_e32 vcc, s64, v0
	s_nop 1
	v_cndmask_b32_e32 v83, v252, v83, vcc
	v_cmp_lt_i32_e32 vcc, s6, v0
	s_movk_i32 s6, 0xff77
	s_nop 0
	v_cndmask_b32_e32 v67, v252, v67, vcc
	v_cmp_lt_i32_e32 vcc, s6, v0
	s_movk_i32 s6, 0xff57
	s_nop 0
	v_cndmask_b32_e32 v84, v252, v84, vcc
	v_cmp_lt_i32_e32 vcc, s6, v0
	s_movk_i32 s6, 0xff76
	s_nop 0
	v_cndmask_b32_e32 v68, v252, v68, vcc
	v_cmp_lt_i32_e32 vcc, s6, v0
	s_movk_i32 s6, 0xff56
	s_nop 0
	v_cndmask_b32_e32 v85, v252, v85, vcc
	v_cmp_lt_i32_e32 vcc, s6, v0
	s_movk_i32 s6, 0xff75
	s_nop 0
	v_cndmask_b32_e32 v69, v252, v69, vcc
	v_cmp_lt_i32_e32 vcc, s6, v0
	s_movk_i32 s6, 0xff55
	s_nop 0
	v_cndmask_b32_e32 v86, v252, v86, vcc
	v_cmp_lt_i32_e32 vcc, s6, v0
	s_movk_i32 s6, 0xff74
	s_nop 0
	v_cndmask_b32_e32 v70, v252, v70, vcc
	v_cmp_lt_i32_e32 vcc, s6, v0
	s_movk_i32 s6, 0xff54
	s_nop 0
	v_cndmask_b32_e32 v87, v252, v87, vcc
	v_cmp_lt_i32_e32 vcc, s6, v0
	s_movk_i32 s6, 0xff6f
	s_nop 0
	v_cndmask_b32_e32 v71, v252, v71, vcc
	v_cmp_lt_i32_e32 vcc, s6, v0
	s_movk_i32 s6, 0xff4f
	s_nop 0
	v_cndmask_b32_e32 v88, v252, v88, vcc
	v_cmp_lt_i32_e32 vcc, s6, v0
	s_movk_i32 s6, 0xff6e
	s_nop 0
	v_cndmask_b32_e32 v72, v252, v72, vcc
	v_cmp_lt_i32_e32 vcc, s6, v0
	s_movk_i32 s6, 0xff4e
	s_nop 0
	v_cndmask_b32_e32 v89, v252, v89, vcc
	v_cmp_lt_i32_e32 vcc, s6, v0
	s_movk_i32 s6, 0xff6d
	s_nop 0
	v_cndmask_b32_e32 v73, v252, v73, vcc
	v_cmp_lt_i32_e32 vcc, s6, v0
	s_movk_i32 s6, 0xff4d
	s_nop 0
	v_cndmask_b32_e32 v90, v252, v90, vcc
	v_cmp_lt_i32_e32 vcc, s6, v0
	s_movk_i32 s6, 0xff6c
	s_nop 0
	v_cndmask_b32_e32 v74, v252, v74, vcc
	v_cmp_lt_i32_e32 vcc, s6, v0
	s_movk_i32 s6, 0xff4c
	s_nop 0
	v_cndmask_b32_e32 v91, v252, v91, vcc
	v_cmp_lt_i32_e32 vcc, s6, v0
	s_movk_i32 s6, 0xff67
	s_nop 0
	v_cndmask_b32_e32 v75, v252, v75, vcc
	v_cmp_lt_i32_e32 vcc, s6, v0
	s_movk_i32 s6, 0xff47
	s_nop 0
	v_cndmask_b32_e32 v92, v252, v92, vcc
	v_cmp_lt_i32_e32 vcc, s6, v0
	s_movk_i32 s6, 0xff66
	s_nop 0
	v_cndmask_b32_e32 v76, v252, v76, vcc
	v_cmp_lt_i32_e32 vcc, s6, v0
	s_movk_i32 s6, 0xff46
	s_nop 0
	v_cndmask_b32_e32 v93, v252, v93, vcc
	v_cmp_lt_i32_e32 vcc, s6, v0
	s_movk_i32 s6, 0xff65
	s_nop 0
	v_cndmask_b32_e32 v77, v252, v77, vcc
	v_cmp_lt_i32_e32 vcc, s6, v0
	s_movk_i32 s6, 0xff45
	s_nop 0
	v_cndmask_b32_e32 v94, v252, v94, vcc
	v_cmp_lt_i32_e32 vcc, s6, v0
	s_movk_i32 s6, 0xff64
	s_nop 0
	v_cndmask_b32_e32 v78, v252, v78, vcc
	v_cmp_lt_i32_e32 vcc, s6, v0
	s_movk_i32 s6, 0xff44
	s_nop 0
	v_cndmask_b32_e32 v95, v252, v95, vcc
	v_cmp_lt_i32_e32 vcc, s6, v0
	s_nop 1
	v_cndmask_b32_e32 v79, v252, v79, vcc
